# GEMM3 epilogue head: ssq loads of rows 14/15 hoisted to epilogue start (one round trip instead of three), on top of noprio+stffn
# speedup vs baseline: 1.0143x; 1.0143x over previous
; #define PG8_LAS __attribute__((address_space(3)))
;     __device__ __forceinline__ void operator()(const f32x4 (&acc)[2][2][4][2], const Unit& u, int wr, int wc, int fr, int fq) const {
;     ...
;         const float* sq = ssq + u.pm * BM + wr * 64 + fr;
;     ...
;         PG8_LAS float* const T = E - 2048;
;         { const int tid_ = threadIdx.x; if (tid_ < 256) E[1024 + tid_] = 1.0f / sqrtf(ssq[u.pm * BM + tid_] * (1.0f / DM) + EPS);
;           else { const int wv_ = __builtin_amdgcn_readfirstlane(tid_ >> 6) - 4; int l2_ = 2 * (tid_ & 63); asm volatile("" : "+v"(l2_));
;                  const float* src_ = ((wv_ == 3) ? cb : cw + (size_t)wv_ * DFF) + u.pn * 128; typedef float f32x2e __attribute__((ext_vector_type(2)));
;                  *(PG8_LAS f32x2e*)(T + wv_ * 128 + l2_) = *(const f32x2e*)(src_ + l2_); } }
.LBB0_729:
	v_mov_b32_e32 v128, v202
	v_mov_b32_e32 v186, v199
	s_lshl_b32 s98, s76, 8
	s_ashr_i32 s99, s98, 31
	s_lshl_b64 s[98:99], s[98:99], 2
	v_readlane_b32 s100, v255, 7
	v_readlane_b32 s101, v255, 8
	s_add_u32 s98, s100, s98
	s_addc_u32 s99, s101, s99
	v_mov_b32_e32 v250, v199
	v_ashrrev_i32_e32 v251, 31, v199
	v_lshl_add_u64 v[250:251], v[250:251], 2, s[98:99]
	global_load_dword v249, v[250:251], off offset:192
	global_load_dword v252, v[250:251], off offset:704
	s_lshl_b32 s10, s6, 7
	s_and_saveexec_b64 s[6:7], s[4:5]
	s_xor_b64 s[6:7], exec, s[6:7]
	s_cbranch_execz .LBB0_733
	v_mov_b32_e32 v126, v204
	s_load_dwordx4 s[16:19], s[0:1], 0xb8
	v_readfirstlane_b32 s8, v0
	s_lshr_b32 s12, s8, 6
	s_add_i32 s12, s12, -4
	s_cmp_eq_u32 s12, 3
	s_waitcnt lgkmcnt(0)
	s_mov_b64 s[8:9], s[18:19]
	s_cbranch_scc1 .LBB0_732
	s_load_dwordx4 s[16:19], s[0:1], 0xb8
	s_mul_i32 s8, s12, 0xac00
	s_mul_hi_i32 s9, s12, 0xac00
	s_waitcnt lgkmcnt(0)
	s_add_u32 s8, s16, s8
	s_addc_u32 s9, s17, s9

; #define PG8_LAS __attribute__((address_space(3)))
; #define RSTD(ai_, m_) (1.0f / sqrtf(sq[(ai_) * HALF + (m_) * 16] * (1.0f / DM) + EPS))
;     __device__ __forceinline__ void operator()(const f32x4 (&acc)[2][2][4][2], const Unit& u, int wr, int wc, int fr, int fq) const {
;     ...
;         if (fr >= 14) {
; #pragma unroll
;             for (int ai = 0; ai < 2; ++ai)
; #pragma unroll
;                 for (int n = 0; n < 2; ++n) *(PG8_LAS f32x4*)(E + ((ai * 2 + wr) * 2 + (fr - 14)) * 128 + jl + 4 * n) = acc[ai][0][3][n] * RSTD(ai, 3);
;             if (!sample && wr == 1) {
; #pragma unroll
;                 for (int n = 0; n < 2; ++n) { const f32x4 gh = acc[1][0][3][n] * RSTD(1, 3); *(f32x4*)(fix + ((size_t)u.pm * 2 + (fr - 14)) * DFF + j0 + 4 * n) = gh;
;                     if ((u.pm & 7) == 7) *(f32x4*)(out + O_PFFN + ((size_t)(u.pm >> 3) * 2 + (fr - 14)) * DFF + j0 + 4 * n) = gh; }
.LBB0_735:
	s_or_b64 exec, exec, s[8:9]
	s_cmp_lt_i32 s76, 32
	s_cselect_b64 s[80:81], -1, 0
	s_cmp_gt_i32 s76, 31
	s_cselect_b64 s[22:23], -1, 0
	v_cmp_gt_i32_e32 vcc, 14, v186
	s_and_saveexec_b64 s[6:7], vcc
	s_xor_b64 s[6:7], exec, s[6:7]
	s_and_b64 s[78:79], s[38:39], s[80:81]
	s_or_saveexec_b64 s[8:9], s[6:7]
	v_lshl_add_u32 v216, v128, 3, s33
	v_add_u32_e32 v184, s10, v216
	s_xor_b64 exec, exec, s[8:9]
	s_cbranch_execz .LBB0_745
	s_ashr_i32 s75, s74, 31
	s_lshl_b64 s[6:7], s[74:75], 2
	v_readlane_b32 s10, v255, 7
	s_add_u32 s6, s10, s6
	v_readlane_b32 s10, v255, 8
	s_addc_u32 s7, s10, s7
	v_ashrrev_i32_e32 v187, 31, v186
	v_lshl_add_u64 v[130:131], v[186:187], 2, s[6:7]
	s_nop 1
	v_mov_b32_e32 v126, v249
	v_readlane_b32 s6, v255, 2
	s_and_b64 s[10:11], s[38:39], s[80:81]
	s_waitcnt vmcnt(0)
	v_fmamk_f32 v126, v126, 0x39800000, v210
	v_cmp_gt_f32_e32 vcc, s27, v126
	v_mul_f32_e32 v127, 0x4f800000, v126
	v_add_lshl_u32 v133, s6, v186, 9
	v_cndmask_b32_e32 v126, v126, v127, vcc
	v_sqrt_f32_e32 v127, v126
	s_nop 0
	v_add_u32_e32 v128, -1, v127
	v_fma_f32 v129, -v128, v127, v126
	v_cmp_ge_f32_e64 s[6:7], 0, v129
	v_add_u32_e32 v129, 1, v127
	s_nop 0
	v_cndmask_b32_e64 v128, v127, v128, s[6:7]
	v_fma_f32 v127, -v129, v127, v126
	v_cmp_lt_f32_e64 s[6:7], 0, v127
	s_nop 1
	v_cndmask_b32_e64 v127, v128, v129, s[6:7]
	v_mul_f32_e32 v128, 0x37800000, v127
	v_cndmask_b32_e32 v127, v127, v128, vcc
	v_cmp_class_f32_e32 vcc, v126, v211
	s_nop 1
	v_cndmask_b32_e32 v126, v127, v126, vcc
	v_div_scale_f32 v127, s[6:7], v126, v126, 1.0
	v_rcp_f32_e32 v128, v127
	s_nop 0
	v_fma_f32 v129, -v127, v128, 1.0
	v_fmac_f32_e32 v128, v129, v128
	v_div_scale_f32 v129, vcc, 1.0, v126, 1.0
	v_mul_f32_e32 v132, v129, v128
	v_fma_f32 v134, -v127, v132, v129
	v_fmac_f32_e32 v132, v134, v128
	v_fma_f32 v127, -v127, v132, v129
	v_div_fmas_f32 v127, v127, v128, v132
	v_div_fixup_f32 v132, v127, v126, 1.0
	v_lshlrev_b32_e32 v134, 2, v216
	v_pk_mul_f32 v[128:129], v[112:113], v[132:133] op_sel_hi:[1,0]
	v_pk_mul_f32 v[126:127], v[110:111], v[132:133] op_sel_hi:[1,0]
	v_add3_u32 v136, s61, v133, v134
	ds_write_b128 v136, v[126:129]
	v_pk_mul_f32 v[128:129], v[48:49], v[132:133] op_sel_hi:[1,0]
	v_pk_mul_f32 v[126:127], v[46:47], v[132:133] op_sel_hi:[1,0]
	ds_write_b128 v136, v[126:129] offset:16
	s_nop 1
	v_mov_b32_e32 v126, v252
	s_waitcnt vmcnt(0)
	v_fmamk_f32 v126, v126, 0x39800000, v210
	v_cmp_gt_f32_e32 vcc, s27, v126
	v_mul_f32_e32 v127, 0x4f800000, v126
	s_nop 0
	v_cndmask_b32_e32 v126, v126, v127, vcc
	v_sqrt_f32_e32 v127, v126
	s_nop 0
	v_add_u32_e32 v128, -1, v127
	v_fma_f32 v129, -v128, v127, v126
	v_cmp_ge_f32_e64 s[6:7], 0, v129
	v_add_u32_e32 v129, 1, v127
	s_nop 0
	v_cndmask_b32_e64 v128, v127, v128, s[6:7]
	v_fma_f32 v127, -v129, v127, v126
	v_cmp_lt_f32_e64 s[6:7], 0, v127
	s_nop 1
	v_cndmask_b32_e64 v127, v128, v129, s[6:7]
	v_mul_f32_e32 v128, 0x37800000, v127
	v_cndmask_b32_e32 v127, v127, v128, vcc
	v_cmp_class_f32_e32 vcc, v126, v211
	s_nop 1
	v_cndmask_b32_e32 v126, v127, v126, vcc
	v_div_scale_f32 v127, s[6:7], v126, v126, 1.0
	v_rcp_f32_e32 v128, v127
	v_readlane_b32 s6, v255, 18
	v_fma_f32 v129, -v127, v128, 1.0
	v_fmac_f32_e32 v128, v129, v128
	v_div_scale_f32 v129, vcc, 1.0, v126, 1.0
	v_mul_f32_e32 v132, v129, v128
	v_fma_f32 v135, -v127, v132, v129
	v_fmac_f32_e32 v132, v135, v128
	v_fma_f32 v127, -v127, v132, v129
	v_div_fmas_f32 v127, v127, v128, v132
	v_div_fixup_f32 v132, v127, v126, 1.0
	v_pk_mul_f32 v[128:129], v[80:81], v[132:133] op_sel_hi:[1,0]
	v_pk_mul_f32 v[126:127], v[78:79], v[132:133] op_sel_hi:[1,0]
	v_add3_u32 v133, s6, v133, v134
	ds_write_b128 v133, v[126:129]
	v_pk_mul_f32 v[134:135], v[16:17], v[132:133] op_sel_hi:[1,0]
	v_pk_mul_f32 v[132:133], v[14:15], v[132:133] op_sel_hi:[1,0]
	s_mov_b64 s[6:7], 0
	s_andn2_b64 vcc, exec, s[10:11]
	ds_write_b128 v136, v[132:135] offset:2064
	s_cbranch_vccnz .LBB0_744
	v_add_u32_e32 v178, -14, v186
	s_ashr_i32 s77, s76, 31
	v_lshl_add_u64 v[132:133], s[76:77], 1, v[178:179]
	v_mov_b64_e32 v[134:135], s[42:43]
	v_mad_u64_u32 v[134:135], s[6:7], v132, s26, v[134:135]
	v_ashrrev_i32_e32 v185, 31, v184
	v_mad_i32_i24 v135, v133, s26, v135
	s_and_b32 s6, s76, 7
	v_lshl_add_u64 v[132:133], v[184:185], 2, v[134:135]
	s_cmp_lg_u32 s6, 7
	s_mov_b64 s[6:7], -1
	global_store_dwordx4 v[132:133], v[126:129], off
	s_cbranch_scc0 .LBB0_741
	s_nop 1
	v_mov_b32_e32 v134, v252
	s_waitcnt vmcnt(0)
	v_fmamk_f32 v134, v134, 0x39800000, v210
	v_mul_f32_e32 v135, 0x4f800000, v134
	v_cmp_gt_f32_e32 vcc, s27, v134
	s_nop 1
	v_cndmask_b32_e32 v134, v134, v135, vcc
	v_sqrt_f32_e32 v135, v134
	s_nop 0
	v_add_u32_e32 v136, -1, v135
	v_add_u32_e32 v137, 1, v135
	v_fma_f32 v138, -v136, v135, v134
	v_fma_f32 v139, -v137, v135, v134
	v_cmp_ge_f32_e64 s[6:7], 0, v138
	s_nop 1
	v_cndmask_b32_e64 v135, v135, v136, s[6:7]
	v_cmp_lt_f32_e64 s[6:7], 0, v139
	s_nop 1
	v_cndmask_b32_e64 v135, v135, v137, s[6:7]
	v_mul_f32_e32 v136, 0x37800000, v135
	v_cndmask_b32_e32 v135, v135, v136, vcc
	v_cmp_class_f32_e32 vcc, v134, v211
	s_nop 1
	v_cndmask_b32_e32 v134, v135, v134, vcc
	v_div_scale_f32 v135, s[6:7], v134, v134, 1.0
	v_rcp_f32_e32 v136, v135
	v_div_scale_f32 v137, vcc, 1.0, v134, 1.0
	s_mov_b64 s[6:7], 0
	v_fma_f32 v138, -v135, v136, 1.0
	v_fmac_f32_e32 v136, v138, v136
	v_mul_f32_e32 v138, v137, v136
	v_fma_f32 v139, -v135, v138, v137
	v_fmac_f32_e32 v138, v139, v136
	v_fma_f32 v135, -v135, v138, v137
	v_div_fmas_f32 v135, v135, v136, v138
	v_div_fixup_f32 v134, v135, v134, 1.0
	v_pk_mul_f32 v[136:137], v[16:17], v[134:135] op_sel_hi:[1,0]
	v_pk_mul_f32 v[134:135], v[14:15], v[134:135] op_sel_hi:[1,0]
	global_store_dwordx4 v[132:133], v[134:137], off offset:16
; #define RSTD(ai_, m_) (1.0f / sqrtf(sq[(ai_) * HALF + (m_) * 16] * (1.0f / DM) + EPS))
;     __device__ __forceinline__ void operator()(const f32x4 (&acc)[2][2][4][2], const Unit& u, int wr, int wc, int fr, int fq) const {
;     ...
;                 for (int n = 0; n < 2; ++n) { const f32x4 gh = acc[1][0][3][n] * RSTD(1, 3); *(f32x4*)(fix + ((size_t)u.pm * 2 + (fr - 14)) * DFF + j0 + 4 * n) = gh;
;                     if ((u.pm & 7) == 7) *(f32x4*)(out + O_PFFN + ((size_t)(u.pm >> 3) * 2 + (fr - 14)) * DFF + j0 + 4 * n) = gh; }
.LBB0_741:
	s_andn2_b64 vcc, exec, s[6:7]
	s_cbranch_vccnz .LBB0_743
	s_ashr_i32 s6, s76, 3
	s_ashr_i32 s7, s6, 31
	v_lshl_add_u64 v[134:135], s[6:7], 1, v[178:179]
	v_readlane_b32 s6, v255, 16
	v_readlane_b32 s7, v255, 17
	v_lshlrev_b64 v[138:139], 2, v[184:185]
	s_nop 0
	v_mov_b64_e32 v[136:137], s[6:7]
	v_mad_u64_u32 v[136:137], s[6:7], v134, s26, v[136:137]
	v_mad_i32_i24 v137, v135, s26, v137
	v_lshl_add_u64 v[136:137], v[136:137], 0, v[138:139]
	global_store_dwordx4 v[136:137], v[126:129], off
	s_nop 1
	s_nop 0
	v_mov_b64_e32 v[126:127], s[34:35]
	v_mad_u64_u32 v[126:127], s[6:7], v134, s26, v[126:127]
	v_mad_i32_i24 v127, v135, s26, v127
	v_lshl_add_u64 v[126:127], v[126:127], 0, v[138:139]
	v_mov_b32_e32 v128, v252
	s_waitcnt vmcnt(0)
	v_fmamk_f32 v128, v128, 0x39800000, v210
	v_mul_f32_e32 v129, 0x4f800000, v128
	v_cmp_gt_f32_e32 vcc, s27, v128
	s_nop 1
	v_cndmask_b32_e32 v128, v128, v129, vcc
	v_sqrt_f32_e32 v129, v128
	s_nop 0
	v_add_u32_e32 v130, -1, v129
	v_add_u32_e32 v131, 1, v129
	v_fma_f32 v134, -v130, v129, v128
	v_fma_f32 v135, -v131, v129, v128
	v_cmp_ge_f32_e64 s[6:7], 0, v134
	s_nop 1
	v_cndmask_b32_e64 v129, v129, v130, s[6:7]
	v_cmp_lt_f32_e64 s[6:7], 0, v135
	s_nop 1
	v_cndmask_b32_e64 v129, v129, v131, s[6:7]
	v_mul_f32_e32 v130, 0x37800000, v129
	v_cndmask_b32_e32 v129, v129, v130, vcc
	v_cmp_class_f32_e32 vcc, v128, v211
	s_nop 1
	v_cndmask_b32_e32 v128, v129, v128, vcc
	v_div_scale_f32 v129, s[6:7], v128, v128, 1.0
	v_rcp_f32_e32 v130, v129
	v_div_scale_f32 v131, vcc, 1.0, v128, 1.0
	v_fma_f32 v134, -v129, v130, 1.0
	v_fmac_f32_e32 v130, v134, v130
	v_mul_f32_e32 v134, v131, v130
	v_fma_f32 v135, -v129, v134, v131
	v_fmac_f32_e32 v134, v135, v130
	v_fma_f32 v129, -v129, v134, v131
	v_div_fmas_f32 v129, v129, v130, v134
	v_add_co_u32_e32 v130, vcc, 0x9630000, v126
	v_div_fixup_f32 v126, v129, v128, 1.0
	s_nop 0
	v_addc_co_u32_e32 v131, vcc, 0, v127, vcc
	v_pk_mul_f32 v[128:129], v[16:17], v[126:127] op_sel_hi:[1,0]
	v_pk_mul_f32 v[126:127], v[14:15], v[126:127] op_sel_hi:[1,0]
	global_store_dwordx4 v[132:133], v[126:129], off offset:16
	global_store_dwordx4 v[130:131], v[126:129], off offset:16
